# P6 sample rows: conv-state loads for rows 4/8/12 of each 16-row batch issued at the batch top (one wait) instead of three exposed load+wait points
# speedup vs baseline: 1.0056x; 1.0056x over previous
; __device__ __forceinline__ void act_item(int item, u16* UP, const u16* HALO, const float* sconv, const float* wconv, const float* bconv, float* out, int lane) {
;     ...
;     for (int tb = 0; tb < 64; tb += 16) {
;         unsigned gw[16], vw[16];
; #pragma unroll
;         for (int t = 0; t < 16; ++t) { const size_t row = (size_t)rb * 64 + tb + t; gw[t] = *(const unsigned*)(UP + row * FF2 + j0); vw[t] = *(const unsigned*)(UP + row * FF2 + FF + j0); }
; #pragma unroll
;         for (int t = 0; t < 16; ++t) {
;             const int row = rb * 64 + tb + t;
;             if (sample && (t & 3) == 0) { const int ns = (row - TP) >> 2; const float* s0 = sconv + (size_t)ns * 2 * FF2;
.LBB0_775:
	v_lshl_add_u64 v[60:61], s[66:67], 0, v[44:45]
	v_add_co_u32_e32 v46, vcc, 0x4300000, v60
	s_nop 1
	v_addc_co_u32_e32 v47, vcc, 0, v61, vcc
	v_add_co_u32_e32 v56, vcc, 0x4301000, v60
	s_nop 1
	v_addc_co_u32_e32 v57, vcc, 0, v61, vcc
	v_add_co_u32_e32 v58, vcc, 0x4302000, v60
	s_nop 1
	v_addc_co_u32_e32 v59, vcc, 0, v61, vcc
	v_add_co_u32_e32 v62, vcc, 0x4304000, v60
	s_nop 1
	v_addc_co_u32_e32 v63, vcc, 0, v61, vcc
	v_add_co_u32_e32 v64, vcc, 0x4305000, v60
	s_nop 1
	v_addc_co_u32_e32 v65, vcc, 0, v61, vcc
	v_add_co_u32_e32 v66, vcc, 0x4306000, v60
	s_nop 1
	v_addc_co_u32_e32 v67, vcc, 0, v61, vcc
	v_add_co_u32_e32 v68, vcc, 0x4308000, v60
	s_nop 1
	v_addc_co_u32_e32 v69, vcc, 0, v61, vcc
	v_add_co_u32_e32 v70, vcc, 0x4309000, v60
	s_nop 1
	v_addc_co_u32_e32 v71, vcc, 0, v61, vcc
	global_load_dword v47, v[46:47], off
	s_nop 0
	global_load_dword v46, v[56:57], off offset:1536
	s_nop 0
	global_load_dword v58, v[58:59], off offset:3072
	s_nop 0
	global_load_dword v59, v[62:63], off offset:512
	global_load_dword v56, v[64:65], off offset:2048
	global_load_dword v57, v[66:67], off offset:3584
	global_load_dword v87, v[68:69], off offset:1024
	global_load_dword v88, v[70:71], off offset:2560
	v_add_co_u32_e32 v62, vcc, 0x430b000, v60
	s_nop 1
	v_addc_co_u32_e32 v63, vcc, 0, v61, vcc
	v_add_co_u32_e32 v64, vcc, 0x430c000, v60
	s_nop 1
	v_addc_co_u32_e32 v65, vcc, 0, v61, vcc
	v_add_co_u32_e32 v66, vcc, 0x430d000, v60
	s_nop 1
	v_addc_co_u32_e32 v67, vcc, 0, v61, vcc
	v_add_co_u32_e32 v68, vcc, 0x430f000, v60
	s_nop 1
	v_addc_co_u32_e32 v69, vcc, 0, v61, vcc
	v_add_co_u32_e32 v70, vcc, 0x4310000, v60
	s_nop 1
	v_addc_co_u32_e32 v71, vcc, 0, v61, vcc
	v_add_co_u32_e32 v72, vcc, 0x4311000, v60
	s_nop 1
	v_addc_co_u32_e32 v73, vcc, 0, v61, vcc
	v_add_co_u32_e32 v74, vcc, 0x4313000, v60
	s_nop 1
	v_addc_co_u32_e32 v75, vcc, 0, v61, vcc
	v_add_co_u32_e32 v76, vcc, 0x4314000, v60
	s_nop 1
	v_addc_co_u32_e32 v77, vcc, 0, v61, vcc
	global_load_dword v86, v[62:63], off
	global_load_dword v85, v[64:65], off offset:1536
	global_load_dword v83, v[66:67], off offset:3072
	global_load_dword v84, v[68:69], off offset:512
	global_load_dword v81, v[70:71], off offset:2048
	global_load_dword v82, v[72:73], off offset:3584
	global_load_dword v79, v[74:75], off offset:1024
	global_load_dword v80, v[76:77], off offset:2560
	v_add_co_u32_e32 v62, vcc, 0x4316000, v60
	s_nop 1
	v_addc_co_u32_e32 v63, vcc, 0, v61, vcc
	v_add_co_u32_e32 v64, vcc, 0x4317000, v60
	s_nop 1
	v_addc_co_u32_e32 v65, vcc, 0, v61, vcc
	v_add_co_u32_e32 v66, vcc, 0x4318000, v60
	s_nop 1
	v_addc_co_u32_e32 v67, vcc, 0, v61, vcc
	v_add_co_u32_e32 v68, vcc, 0x431a000, v60
	s_nop 1
	v_addc_co_u32_e32 v69, vcc, 0, v61, vcc
	v_add_co_u32_e32 v70, vcc, 0x431b000, v60
	s_nop 1
	v_addc_co_u32_e32 v71, vcc, 0, v61, vcc
	v_add_co_u32_e32 v90, vcc, 0x431c000, v60
	s_nop 1
	v_addc_co_u32_e32 v91, vcc, 0, v61, vcc
	v_add_co_u32_e32 v92, vcc, 0x431e000, v60
	s_nop 1
	v_addc_co_u32_e32 v93, vcc, 0, v61, vcc
	v_add_co_u32_e32 v94, vcc, 0x431f000, v60
	s_nop 1
	v_addc_co_u32_e32 v95, vcc, 0, v61, vcc
	global_load_dword v78, v[62:63], off
	global_load_dword v77, v[64:65], off offset:1536
	global_load_dword v75, v[66:67], off offset:3072
	global_load_dword v76, v[68:69], off offset:512
	global_load_dword v73, v[70:71], off offset:2048
	global_load_dword v74, v[90:91], off offset:3584
	s_nop 0
	global_load_dword v71, v[92:93], off offset:1024
	global_load_dword v72, v[94:95], off offset:2560
	v_add_co_u32_e32 v62, vcc, 0x4321000, v60
	s_nop 1
	v_addc_co_u32_e32 v63, vcc, 0, v61, vcc
	v_add_co_u32_e32 v64, vcc, 0x4322000, v60
	s_nop 1
	v_addc_co_u32_e32 v65, vcc, 0, v61, vcc
	v_add_co_u32_e32 v66, vcc, 0x4323000, v60
	s_nop 1
	v_addc_co_u32_e32 v67, vcc, 0, v61, vcc
	v_add_co_u32_e32 v90, vcc, 0x4325000, v60
	s_nop 1
	v_addc_co_u32_e32 v91, vcc, 0, v61, vcc
	v_add_co_u32_e32 v92, vcc, 0x4326000, v60
	s_nop 1
	v_addc_co_u32_e32 v93, vcc, 0, v61, vcc
	v_add_co_u32_e32 v94, vcc, 0x4327000, v60
	s_nop 1
	v_addc_co_u32_e32 v95, vcc, 0, v61, vcc
	v_add_co_u32_e32 v96, vcc, 0x4329000, v60
	s_nop 1
	v_addc_co_u32_e32 v97, vcc, 0, v61, vcc
	v_add_co_u32_e32 v60, vcc, 0x432a000, v60
	s_nop 1
	v_addc_co_u32_e32 v61, vcc, 0, v61, vcc
	global_load_dword v70, v[62:63], off
	global_load_dword v69, v[64:65], off offset:1536
	s_nop 0
	global_load_dword v66, v[66:67], off offset:3072
	s_nop 0
	global_load_dword v67, v[90:91], off offset:512
	global_load_dword v64, v[92:93], off offset:2048
	global_load_dword v65, v[94:95], off offset:3584
	global_load_dword v1, v[96:97], off offset:1024
	global_load_dword v68, v[60:61], off offset:2560
	v_cndmask_b32_e64 v60, 0, 1, s[58:59]
	v_cmp_ne_u32_e64 s[6:7], 1, v60
	s_andn2_b64 vcc, exec, s[58:59]
	s_cbranch_vccnz .LBB0_777
; __device__ __forceinline__ void act_item(int item, u16* UP, const u16* HALO, const float* sconv, const float* wconv, const float* bconv, float* out, int lane) {
;     ...
;             if (sample && (t & 3) == 0) { const int ns = (row - TP) >> 2; const float* s0 = sconv + (size_t)ns * 2 * FF2;
;                 const f32x2 a = *(const f32x2*)(s0 + j0), b = *(const f32x2*)(s0 + FF + j0), c = *(const f32x2*)(s0 + FF2 + j0), dd = *(const f32x2*)(s0 + FF2 + FF + j0);
;                 g2[0] = a.x; g2[1] = a.y; v2[0] = b.x; v2[1] = b.y; g1[0] = c.x; g1[1] = c.y; v1[0] = dd.x; v1[1] = dd.y; }
	s_add_i32 s0, s81, s83
	s_addk_i32 s0, 0xc000
	s_ashr_i32 s0, s0, 2
	s_mul_hi_i32 s1, s0, 0xb000
	s_mul_i32 s0, s0, 0xb000
	s_add_u32 s0, s22, s0
	s_addc_u32 s1, s23, s1
	v_lshl_add_u64 v[48:49], v[2:3], 2, s[0:1]
	v_add_co_u32_e32 v50, vcc, 0x2000, v48
	s_nop 1
	v_addc_co_u32_e32 v51, vcc, 0, v49, vcc
	v_add_co_u32_e32 v52, vcc, 0x5000, v48
	s_nop 1
	v_addc_co_u32_e32 v53, vcc, 0, v49, vcc
	v_add_co_u32_e32 v54, vcc, 0x8000, v48
	s_nop 1
	v_addc_co_u32_e32 v55, vcc, 0, v49, vcc
	s_add_u32 s68, s0, 0xb000
	s_addc_u32 s69, s1, 0
	v_lshl_add_u64 v[100:101], v[2:3], 2, s[68:69]
	global_load_dwordx2 v[100:101], v[100:101], off
	s_add_u32 s68, s0, 0xdc00
	s_addc_u32 s69, s1, 0
	v_lshl_add_u64 v[102:103], v[2:3], 2, s[68:69]
	global_load_dwordx2 v[102:103], v[102:103], off
	s_add_u32 s68, s0, 0x10800
	s_addc_u32 s69, s1, 0
	v_lshl_add_u64 v[104:105], v[2:3], 2, s[68:69]
	global_load_dwordx2 v[104:105], v[104:105], off
	s_add_u32 s68, s0, 0x13400
	s_addc_u32 s69, s1, 0
	v_lshl_add_u64 v[106:107], v[2:3], 2, s[68:69]
	global_load_dwordx2 v[106:107], v[106:107], off
	s_add_u32 s68, s0, 0x16000
	s_addc_u32 s69, s1, 0
	v_lshl_add_u64 v[108:109], v[2:3], 2, s[68:69]
	global_load_dwordx2 v[108:109], v[108:109], off
	s_add_u32 s68, s0, 0x18c00
	s_addc_u32 s69, s1, 0
	v_lshl_add_u64 v[110:111], v[2:3], 2, s[68:69]
	global_load_dwordx2 v[110:111], v[110:111], off
	s_add_u32 s68, s0, 0x1b800
	s_addc_u32 s69, s1, 0
	v_lshl_add_u64 v[112:113], v[2:3], 2, s[68:69]
	global_load_dwordx2 v[112:113], v[112:113], off
	s_add_u32 s68, s0, 0x1e400
	s_addc_u32 s69, s1, 0
	v_lshl_add_u64 v[114:115], v[2:3], 2, s[68:69]
	global_load_dwordx2 v[114:115], v[114:115], off
	s_add_u32 s68, s0, 0x21000
	s_addc_u32 s69, s1, 0
	v_lshl_add_u64 v[116:117], v[2:3], 2, s[68:69]
	global_load_dwordx2 v[116:117], v[116:117], off
	s_add_u32 s68, s0, 0x23c00
	s_addc_u32 s69, s1, 0
	v_lshl_add_u64 v[118:119], v[2:3], 2, s[68:69]
	global_load_dwordx2 v[118:119], v[118:119], off
	s_add_u32 s68, s0, 0x26800
	s_addc_u32 s69, s1, 0
	v_lshl_add_u64 v[120:121], v[2:3], 2, s[68:69]
	global_load_dwordx2 v[120:121], v[120:121], off
	s_add_u32 s68, s0, 0x29400
	s_addc_u32 s69, s1, 0
	v_lshl_add_u64 v[122:123], v[2:3], 2, s[68:69]
	global_load_dwordx2 v[122:123], v[122:123], off
	global_load_dwordx2 v[48:49], v[48:49], off
	s_nop 0
	global_load_dwordx2 v[50:51], v[50:51], off offset:3072
	s_nop 0
	global_load_dwordx2 v[52:53], v[52:53], off offset:2048
	s_nop 0
	global_load_dwordx2 v[54:55], v[54:55], off offset:1024

; __device__ __forceinline__ void act_item(int item, u16* UP, const u16* HALO, const float* sconv, const float* wconv, const float* bconv, float* out, int lane) {
;     ...
;             if (sample && (t & 3) == 0) { const int ns = (row - TP) >> 2; const float* s0 = sconv + (size_t)ns * 2 * FF2;
;                 const f32x2 a = *(const f32x2*)(s0 + j0), b = *(const f32x2*)(s0 + FF + j0), c = *(const f32x2*)(s0 + FF2 + j0), dd = *(const f32x2*)(s0 + FF2 + FF + j0);
;                 g2[0] = a.x; g2[1] = a.y; v2[0] = b.x; v2[1] = b.y; g1[0] = c.x; g1[1] = c.y; v1[0] = dd.x; v1[1] = dd.y; }
.LBB0_783:
	s_and_b64 vcc, exec, s[6:7]
	s_cbranch_vccnz .LBB0_785
	s_add_i32 s68, s81, s83
	s_addk_i32 s68, 0xc004
	s_ashr_i32 s68, s68, 2
	s_mul_hi_i32 s69, s68, 0xb000
	s_mul_i32 s68, s68, 0xb000
	s_add_u32 s68, s22, s68
	s_addc_u32 s69, s23, s69
	v_mov_b32_e32 v58, v100
	v_mov_b32_e32 v59, v101
	v_mov_b32_e32 v60, v102
	v_mov_b32_e32 v61, v103
	v_mov_b32_e32 v52, v104
	v_mov_b32_e32 v53, v105
	v_mov_b32_e32 v56, v106
	v_mov_b32_e32 v57, v107

; __device__ __forceinline__ void act_item(int item, u16* UP, const u16* HALO, const float* sconv, const float* wconv, const float* bconv, float* out, int lane) {
;     ...
;             if (sample && (t & 3) == 0) { const int ns = (row - TP) >> 2; const float* s0 = sconv + (size_t)ns * 2 * FF2;
;                 const f32x2 a = *(const f32x2*)(s0 + j0), b = *(const f32x2*)(s0 + FF + j0), c = *(const f32x2*)(s0 + FF2 + j0), dd = *(const f32x2*)(s0 + FF2 + FF + j0);
;                 g2[0] = a.x; g2[1] = a.y; v2[0] = b.x; v2[1] = b.y; g1[0] = c.x; g1[1] = c.y; v1[0] = dd.x; v1[1] = dd.y; }
.LBB0_791:
	s_and_b64 vcc, exec, s[6:7]
	s_cbranch_vccnz .LBB0_793
	s_add_i32 s68, s81, s83
	s_addk_i32 s68, 0xc008
	s_ashr_i32 s68, s68, 2
	s_mul_hi_i32 s69, s68, 0xb000
	s_mul_i32 s68, s68, 0xb000
	s_add_u32 s68, s22, s68
	s_addc_u32 s69, s23, s69
	v_mov_b32_e32 v56, v108
	v_mov_b32_e32 v57, v109
	v_mov_b32_e32 v60, v110
	v_mov_b32_e32 v61, v111
	v_mov_b32_e32 v50, v112
	v_mov_b32_e32 v51, v113
	v_mov_b32_e32 v58, v114
	v_mov_b32_e32 v59, v115

; __device__ __forceinline__ void act_item(int item, u16* UP, const u16* HALO, const float* sconv, const float* wconv, const float* bconv, float* out, int lane) {
;     ...
;             if (sample && (t & 3) == 0) { const int ns = (row - TP) >> 2; const float* s0 = sconv + (size_t)ns * 2 * FF2;
;                 const f32x2 a = *(const f32x2*)(s0 + j0), b = *(const f32x2*)(s0 + FF + j0), c = *(const f32x2*)(s0 + FF2 + j0), dd = *(const f32x2*)(s0 + FF2 + FF + j0);
;                 g2[0] = a.x; g2[1] = a.y; v2[0] = b.x; v2[1] = b.y; g1[0] = c.x; g1[1] = c.y; v1[0] = dd.x; v1[1] = dd.y; }
.LBB0_800:
	s_add_i32 s84, s81, s83
	s_add_i32 s6, s84, 0xffffc00c
	s_ashr_i32 s6, s6, 2
	s_mul_hi_i32 s7, s6, 0xb000
	s_mul_i32 s6, s6, 0xb000
	s_add_u32 s6, s22, s6
	s_addc_u32 s7, s23, s7
	v_mov_b32_e32 v52, v116
	v_mov_b32_e32 v53, v117
	v_mov_b32_e32 v54, v118
	v_mov_b32_e32 v55, v119
	v_mov_b32_e32 v48, v120
	v_mov_b32_e32 v49, v121
	v_mov_b32_e32 v50, v122
	v_mov_b32_e32 v51, v123
